# attnA: Q fragments kept in v160-175 instead of per-tile LDS re-read
# baseline (speedup 1.0000x reference)
; DI void task_attnA(const P& p, int layer, int task, bf16_t* sm, int dm) {
;     ...
;   const int q0 = qb * 128, qmin = q0 + qs * 32, qp = qmin + lr;
;   bf16_t* aq = (bf16_t*)(p.ws + O_AQ);
;   {
;     const bf16_t* qptr = aq + (size_t)(b * S_ + qp) * 512 + h * 128 + c * 64 + lh * 8;
; #pragma unroll
;     for (int ks = 0; ks < 4; ++ks) qlds[ks * 64] = *(const bf16x8*)(qptr + ks * 16);
;   }
;   f32x16 O[4];
; #pragma unroll
;   for (int dt = 0; dt < 4; ++dt)
; #pragma unroll
;     for (int i = 0; i < 16; ++i) O[dt][i] = 0.f;
;   float m = -1e30f, l = 0.f;
;   const bf16_t* kg = (const bf16_t*)(p.ws + O_AK) + (size_t)b * S_ * 512 + h * 128;
;   const bf16_t* vg = (const bf16_t*)(p.ws + O_AVT) + (size_t)((b * 4 + h) * 128) * S_;
;   u32x4 rk0, rk1, rv0, rv1;
;     ...
;   const int kt_hi = 2 * qb + 1;
;   A_GLOAD(0, 0) A_GLOAD(1, 0)
.LBB0_974:
	s_or_b64 exec, exec, s[0:1]
	s_mul_i32 s100, s2, 0x210
	s_add_u32 s36, s20, s100
	s_addc_u32 s37, s21, 0
	s_movk_i32 s100, 0x80
	s_mov_b32 s101, 0x40000000
	v_subrev_u32_e32 v247, 64, v195
	v_med3_i32 v249, v247, 0, s100
	v_lshlrev_b32_e32 v249, 2, v249
	global_load_dword v196, v249, s[36:37]
	v_mov_b32_e32 v246, 0xf149f2ca
	v_lshlrev_b32_e32 v244, 2, v195
	v_add_u32_e32 v244, 0x1e000, v244
	s_waitcnt vmcnt(0)
	v_cmp_gt_u32_e64 s[98:99], s101, v247
	s_nop 1
	v_cndmask_b32_e64 v196, v246, v196, s[98:99]
	ds_write_b32 v244, v196
	s_add_i32 s3, s34, -16
	s_lshr_b32 s0, s3, 4
	s_xor_b32 s4, s0, 31
	v_ashrrev_i32_e32 v0, 2, v138
	s_lshl_b32 s5, s4, 7
	v_and_b32_e32 v27, 0xffffffe0, v0
	v_and_b32_e32 v139, 31, v138
	v_add_u32_e32 v28, s5, v27
	s_bfe_u32 s0, s34, 0x20002
	v_or_b32_e32 v0, v28, v139
	v_lshl_add_u32 v0, s0, 12, v0
	s_lshl_b32 s66, s2, 8
	s_lshl_b32 s0, s0, 22
	s_add_u32 s0, s56, s0
	v_ashrrev_i32_e32 v16, 4, v138
	s_addc_u32 s1, s57, 0
	v_ashrrev_i32_e32 v17, 31, v16
	s_add_u32 s0, s0, s66
	v_lshlrev_b64 v[18:19], 10, v[16:17]
	v_lshlrev_b32_e32 v17, 3, v138
	s_addc_u32 s1, s1, 0
	s_lshl_b32 s2, s3, 20
	v_and_b32_e32 v20, 0x78, v17
	s_and_b32 s2, s2, 0xf00000
	v_readlane_b32 s6, v253, 50
	v_lshlrev_b32_e32 v126, 1, v20
	v_ashrrev_i32_e32 v20, 3, v138
	v_readlane_b32 s7, v253, 51
	s_add_u32 s2, s6, s2
	v_ashrrev_i32_e32 v21, 31, v20
	v_ashrrev_i32_e32 v1, 31, v0
	s_addc_u32 s3, s7, 0
	v_lshlrev_b64 v[22:23], 13, v[20:21]
	v_and_b32_e32 v17, 56, v17
	v_ashrrev_i32_e32 v26, 6, v138
	v_lshlrev_b64 v[0:1], 10, v[0:1]
	v_lshl_add_u64 v[22:23], s[2:3], 0, v[22:23]
	v_lshlrev_b32_e32 v128, 1, v17
	v_mov_b32_e32 v129, v193
	v_add_u32_e32 v17, 0x200, v138
	v_and_b32_e32 v140, 1, v26
	v_lshl_add_u64 v[0:1], s[58:59], 0, v[0:1]
	v_lshl_add_u64 v[130:131], v[22:23], 0, v[128:129]
	v_ashrrev_i32_e32 v22, 4, v17
	v_bfe_u32 v137, v138, 5, 1
	v_lshl_add_u64 v[124:125], v[0:1], 0, s[66:67]
	v_lshlrev_b32_e32 v192, 7, v140
	v_ashrrev_i32_e32 v23, 31, v22
	v_lshl_add_u64 v[0:1], v[124:125], 0, v[192:193]
	v_lshlrev_b32_e32 v192, 4, v137
	v_lshl_add_u64 v[18:19], s[0:1], 0, v[18:19]
	v_mov_b32_e32 v127, v193
	v_lshlrev_b64 v[24:25], 10, v[22:23]
	v_lshl_add_u64 v[12:13], v[0:1], 0, v[192:193]
	v_lshl_add_u64 v[18:19], v[18:19], 0, v[126:127]
	v_lshl_add_u64 v[24:25], s[0:1], 0, v[24:25]
	global_load_dwordx4 v[0:3], v[12:13], off
	global_load_dwordx4 v[4:7], v[12:13], off offset:32
	global_load_dwordx4 v[8:11], v[12:13], off offset:64
	s_nop 0
	global_load_dwordx4 v[12:15], v[12:13], off offset:96
	v_lshl_add_u64 v[24:25], v[24:25], 0, v[126:127]
	global_load_dwordx4 v[96:99], v[18:19], off
	global_load_dwordx4 v[104:107], v[24:25], off
	v_ashrrev_i32_e32 v18, 3, v17
	v_ashrrev_i32_e32 v19, 31, v18
	v_lshlrev_b64 v[24:25], 13, v[18:19]
	v_lshl_add_u64 v[24:25], s[2:3], 0, v[24:25]
	v_lshl_add_u64 v[132:133], v[24:25], 0, v[128:129]
	global_load_dwordx4 v[100:103], v[130:131], off
	global_load_dwordx4 v[108:111], v[132:133], off
	v_and_b32_e32 v17, 63, v138
	v_lshlrev_b32_e32 v19, 12, v26
	v_lshlrev_b32_e32 v17, 4, v17
	v_readlane_b32 s3, v255, 5
	v_mov_b32_e32 v48, v193
	v_mov_b32_e32 v49, v193
	s_movk_i32 s2, 0x110
	v_add3_u32 v143, s3, v19, v17
	v_lshl_add_u64 v[134:135], s[0:1], 0, v[126:127]
	s_sub_i32 s0, s5, 59
	v_mov_b32_e32 v50, v193
	v_mul_lo_u32 v129, v16, s2
	v_mul_lo_u32 v141, v20, s89
	v_add_u32_e32 v142, 64, v16
	v_mul_lo_u32 v145, v22, s2
	v_mul_lo_u32 v146, v18, s89
	v_add_u32_e32 v147, 64, v22
	v_or_b32_e32 v148, 31, v28
	v_add_u32_e32 v149, 0xffffff41, v28
	s_lshl_b32 s6, s4, 1
	s_mov_b32 s66, 0
	v_add3_u32 v127, s0, v27, v139
	v_mov_b32_e32 v51, v193
	v_mov_b32_e32 v52, v193
	v_mov_b32_e32 v53, v193
	v_mov_b32_e32 v54, v193
	v_mov_b32_e32 v55, v193
	v_mov_b32_e32 v56, v193
	s_waitcnt vmcnt(7)
	ds_write_b128 v143, v[0:3]
	s_waitcnt vmcnt(6)
	ds_write_b128 v143, v[4:7] offset:1024
	s_waitcnt vmcnt(5)
	ds_write_b128 v143, v[8:11] offset:2048
	s_waitcnt vmcnt(4)
	ds_write_b128 v143, v[12:15] offset:3072
	v_mov_b64_e32 v[160:161], v[0:1]
	v_mov_b64_e32 v[162:163], v[2:3]
	v_mov_b64_e32 v[164:165], v[4:5]
	v_mov_b64_e32 v[166:167], v[6:7]
	v_mov_b64_e32 v[168:169], v[8:9]
	v_mov_b64_e32 v[170:171], v[10:11]
	v_mov_b64_e32 v[172:173], v[12:13]
	v_mov_b64_e32 v[174:175], v[14:15]
	v_mov_b32_e32 v57, v193
	v_mov_b32_e32 v58, v193
	v_mov_b32_e32 v59, v193
	v_mov_b32_e32 v60, v193
	v_mov_b32_e32 v61, v193
	v_mov_b32_e32 v62, v193
	v_mov_b32_e32 v63, v193
	v_mov_b64_e32 v[32:33], v[48:49]
	v_mov_b64_e32 v[16:17], v[48:49]
	v_mov_b64_e32 v[0:1], v[48:49]
	v_lshlrev_b32_e32 v144, 6, v140
	s_add_i32 s7, s6, 2
	v_mov_b32_e32 v154, 0xf149f2ca
	v_mov_b32_e32 v151, 0
	v_mov_b64_e32 v[34:35], v[50:51]
	v_mov_b64_e32 v[36:37], v[52:53]
	v_mov_b64_e32 v[38:39], v[54:55]
	v_mov_b64_e32 v[40:41], v[56:57]
	v_mov_b64_e32 v[42:43], v[58:59]
	v_mov_b64_e32 v[44:45], v[60:61]
	v_mov_b64_e32 v[46:47], v[62:63]
	v_mov_b64_e32 v[18:19], v[50:51]
	v_mov_b64_e32 v[20:21], v[52:53]
	v_mov_b64_e32 v[22:23], v[54:55]
	v_mov_b64_e32 v[24:25], v[56:57]
	v_mov_b64_e32 v[26:27], v[58:59]
	v_mov_b64_e32 v[28:29], v[60:61]
	v_mov_b64_e32 v[30:31], v[62:63]
	v_mov_b64_e32 v[2:3], v[50:51]
	v_mov_b64_e32 v[4:5], v[52:53]
	v_mov_b64_e32 v[6:7], v[54:55]
	v_mov_b64_e32 v[8:9], v[56:57]
	v_mov_b64_e32 v[10:11], v[58:59]
	v_mov_b64_e32 v[12:13], v[60:61]
	v_mov_b64_e32 v[14:15], v[62:63]
	s_mov_b32 s8, s66
	s_branch .LBB0_978

; #define MFMA32(a, b, c) __builtin_amdgcn_mfma_f32_32x32x16_bf16((a), (b), (c), 0, 0, 0)
; DI float ex2(float x) { return __builtin_amdgcn_exp2f(x); }
; DI float xor32(float v) { return __shfl_xor(v, 32); }
; template <int NDT, int MODE, bool ALLON>
; DI void attn_tile(const bf16_t* Kl, int kst, const bf16_t* Vl, const bf16x8 (&q)[4], f32x16 (&O)[NDT], float& m, float& l,
;                   int kbase, int qp, int win, float cbias, const float* tab, bool lane_on) {
;     ...
;   for (int ks = 0; ks < 4; ++ks) {
;     const bf16x8 k0 = *(const bf16x8*)(Kl + lr * kst + ks * 16 + lh * 8);
;     const bf16x8 k1 = *(const bf16x8*)(Kl + (32 + lr) * kst + ks * 16 + lh * 8);
;     s[0] = MFMA32(k0, q[ks], s[0]);
;     s[1] = MFMA32(k1, q[ks], s[1]);
;   }
;   float alpha, psum = 0.f;
;   if (MODE == 0) {
;     float tmax = fmaxf(s[0][0], s[1][0]);
; #pragma unroll
;     for (int i = 1; i < 16; ++i) tmax = fmaxf(tmax, fmaxf(s[0][i], s[1][i]));
;     tmax = fmaxf(tmax, xor32(tmax)) + cbias;
;     if (!ALLON) tmax = lane_on ? tmax : -1e30f;
;     const float mn = fmaxf(m, tmax);
;     alpha = ex2(m - mn);
;     m = mn;
;     const float mc = (ALLON || lane_on) ? mn - cbias : 1e30f;
; #pragma unroll
;     for (int st = 0; st < 2; ++st)
; #pragma unroll
;       for (int i = 0; i < 16; ++i) { const float pe = ex2(s[st][i] - mc); psum += pe; s[st][i] = pe; }
; DI void task_attnA(const P& p, int layer, int task, bf16_t* sm, int dm) {
;     ...
;     if (kt * 64 <= qmin + 31) {
;       bf16x8 q[4];
; #pragma unroll
;       for (int ks = 0; ks < 4; ++ks) q[ks] = qlds[ks * 64];
;       if (kt * 64 + 63 + 128 <= qmin)
;         attn_tile<4, 0, true>(Kl + c * 64, 136, Vl, q, O, m, l, kt * 64, qp, 0, tab[128], tab, true);
.LBB0_980:
	v_cmp_le_i32_e32 vcc, s66, v148
	s_waitcnt lgkmcnt(0)
	s_barrier
	s_and_saveexec_b64 s[0:1], vcc
	s_cbranch_execz .LBB0_977
	v_cmp_le_i32_e32 vcc, s66, v149
	v_lshl_add_u32 v69, v144, 1, s9
	s_and_saveexec_b64 s[2:3], vcc
	s_xor_b64 s[2:3], exec, s[2:3]
	s_cbranch_execz .LBB0_985
	v_mov_b32_e32 v68, s81
	ds_read_b32 v155, v68
	v_mov_b32_e32 v68, v195
	s_nop 0
	v_and_b32_e32 v153, 31, v68
	v_lshrrev_b32_e32 v68, 2, v68
	v_and_b32_e32 v152, 8, v68
	v_mul_u32_u24_e32 v70, 0x110, v153
	v_lshlrev_b32_e32 v68, 1, v152
	v_add3_u32 v150, v69, v70, v68
	ds_read_b128 v[68:71], v150
	ds_read_b128 v[156:159], v150 offset:32
	s_waitcnt lgkmcnt(1)
	v_mfma_f32_32x32x16_bf16 v[80:95], v[68:71], v[160:163], 0
	ds_read_b128 v[68:71], v150 offset:8704
	s_waitcnt lgkmcnt(1)
	v_mfma_f32_32x32x16_bf16 v[80:95], v[156:159], v[164:167], v[80:95]
	ds_read_b128 v[156:159], v150 offset:8736
	s_waitcnt lgkmcnt(1)
	v_mfma_f32_32x32x16_bf16 v[64:79], v[68:71], v[160:163], 0
	s_waitcnt lgkmcnt(0)
	v_mfma_f32_32x32x16_bf16 v[64:79], v[156:159], v[164:167], v[64:79]
	ds_read_b128 v[120:123], v150 offset:64
	s_waitcnt lgkmcnt(0)
	v_mfma_f32_32x32x16_bf16 v[80:95], v[120:123], v[168:171], v[80:95]
	ds_read_b128 v[120:123], v150 offset:8768
	s_waitcnt lgkmcnt(0)
	v_mfma_f32_32x32x16_bf16 v[64:79], v[120:123], v[168:171], v[64:79]
	ds_read_b128 v[116:119], v150 offset:8800
	s_waitcnt lgkmcnt(0)
	v_mfma_f32_32x32x16_bf16 v[64:79], v[116:119], v[172:175], v[64:79]
	ds_read_b128 v[116:119], v150 offset:96
	s_waitcnt lgkmcnt(0)
	v_mfma_f32_32x32x16_bf16 v[80:95], v[116:119], v[172:175], v[80:95]
	s_nop 8
	v_max3_f32 v112, v64, v65, v66
	v_max3_f32 v112, v112, v67, v68
	v_max3_f32 v112, v112, v69, v70
	v_max3_f32 v112, v112, v71, v72
	v_max3_f32 v112, v112, v73, v74
	v_max3_f32 v112, v112, v75, v76
	v_max3_f32 v112, v112, v77, v78
	v_max_f32_e32 v112, v112, v79
	v_max3_f32 v113, v80, v81, v82
	v_max3_f32 v113, v113, v83, v84
	v_max3_f32 v113, v113, v85, v86
	v_max3_f32 v113, v113, v87, v88
	v_max3_f32 v113, v113, v89, v90
	v_max3_f32 v113, v113, v91, v92
	v_max3_f32 v113, v113, v93, v94
	v_max_f32_e32 v113, v113, v95
	v_max_f32_e32 v112, v112, v113
	v_and_b32_e32 v114, 64, v231
	v_xor_b32_e32 v113, 32, v231
	v_add_u32_e32 v114, 64, v114
	v_cmp_lt_i32_e32 vcc, v113, v114
	s_nop 1
	v_cndmask_b32_e32 v113, v231, v113, vcc
	v_lshlrev_b32_e32 v113, 2, v113
	ds_bpermute_b32 v113, v113, v112
	s_waitcnt lgkmcnt(0)
	v_max_f32_e32 v113, v113, v113
	v_max_f32_e32 v112, v112, v113
	v_add_f32_e32 v112, v155, v112
	v_max_f32_e32 v113, v154, v154
	v_max_f32_e32 v150, v113, v112
	v_sub_f32_e32 v112, v154, v150
	v_exp_f32_e32 v112, v112
	s_nop 0
	v_cmp_neq_f32_e32 vcc, 1.0, v112
	s_cbranch_vccz .LBB0_984
	v_pk_mul_f32 v[62:63], v[62:63], v[112:113] op_sel_hi:[1,0]
	v_pk_mul_f32 v[60:61], v[60:61], v[112:113] op_sel_hi:[1,0]
	v_pk_mul_f32 v[58:59], v[58:59], v[112:113] op_sel_hi:[1,0]
	v_pk_mul_f32 v[56:57], v[56:57], v[112:113] op_sel_hi:[1,0]
	v_pk_mul_f32 v[54:55], v[54:55], v[112:113] op_sel_hi:[1,0]
	v_pk_mul_f32 v[52:53], v[52:53], v[112:113] op_sel_hi:[1,0]
	v_pk_mul_f32 v[50:51], v[50:51], v[112:113] op_sel_hi:[1,0]
	v_pk_mul_f32 v[48:49], v[48:49], v[112:113] op_sel_hi:[1,0]
	v_pk_mul_f32 v[46:47], v[46:47], v[112:113] op_sel_hi:[1,0]
	v_pk_mul_f32 v[44:45], v[44:45], v[112:113] op_sel_hi:[1,0]
	v_pk_mul_f32 v[42:43], v[42:43], v[112:113] op_sel_hi:[1,0]
	v_pk_mul_f32 v[40:41], v[40:41], v[112:113] op_sel_hi:[1,0]
	v_pk_mul_f32 v[38:39], v[38:39], v[112:113] op_sel_hi:[1,0]
	v_pk_mul_f32 v[36:37], v[36:37], v[112:113] op_sel_hi:[1,0]
	v_pk_mul_f32 v[34:35], v[34:35], v[112:113] op_sel_hi:[1,0]
	v_pk_mul_f32 v[32:33], v[32:33], v[112:113] op_sel_hi:[1,0]
	v_pk_mul_f32 v[30:31], v[30:31], v[112:113] op_sel_hi:[1,0]
	v_pk_mul_f32 v[28:29], v[28:29], v[112:113] op_sel_hi:[1,0]
	v_pk_mul_f32 v[26:27], v[26:27], v[112:113] op_sel_hi:[1,0]
	v_pk_mul_f32 v[24:25], v[24:25], v[112:113] op_sel_hi:[1,0]
	v_pk_mul_f32 v[22:23], v[22:23], v[112:113] op_sel_hi:[1,0]
	v_pk_mul_f32 v[20:21], v[20:21], v[112:113] op_sel_hi:[1,0]
	v_pk_mul_f32 v[18:19], v[18:19], v[112:113] op_sel_hi:[1,0]
	v_pk_mul_f32 v[16:17], v[16:17], v[112:113] op_sel_hi:[1,0]
	v_pk_mul_f32 v[14:15], v[14:15], v[112:113] op_sel_hi:[1,0]
	v_pk_mul_f32 v[12:13], v[12:13], v[112:113] op_sel_hi:[1,0]
	v_pk_mul_f32 v[10:11], v[10:11], v[112:113] op_sel_hi:[1,0]
	v_pk_mul_f32 v[8:9], v[8:9], v[112:113] op_sel_hi:[1,0]
	v_pk_mul_f32 v[6:7], v[6:7], v[112:113] op_sel_hi:[1,0]
	v_pk_mul_f32 v[4:5], v[4:5], v[112:113] op_sel_hi:[1,0]
	v_pk_mul_f32 v[2:3], v[2:3], v[112:113] op_sel_hi:[1,0]
	v_pk_mul_f32 v[0:1], v[0:1], v[112:113] op_sel_hi:[1,0]

; #define MFMA32(a, b, c) __builtin_amdgcn_mfma_f32_32x32x16_bf16((a), (b), (c), 0, 0, 0)
; DI float ex2(float x) { return __builtin_amdgcn_exp2f(x); }
; DI float xor32(float v) { return __shfl_xor(v, 32); }
; template <int NDT, int MODE, bool ALLON>
; DI void attn_tile(const bf16_t* Kl, int kst, const bf16_t* Vl, const bf16x8 (&q)[4], f32x16 (&O)[NDT], float& m, float& l,
;                   int kbase, int qp, int win, float cbias, const float* tab, bool lane_on) {
;     ...
;   for (int ks = 0; ks < 4; ++ks) {
;     const bf16x8 k0 = *(const bf16x8*)(Kl + lr * kst + ks * 16 + lh * 8);
;     const bf16x8 k1 = *(const bf16x8*)(Kl + (32 + lr) * kst + ks * 16 + lh * 8);
;     s[0] = MFMA32(k0, q[ks], s[0]);
;     s[1] = MFMA32(k1, q[ks], s[1]);
;   }
;   float alpha, psum = 0.f;
;   if (MODE == 0) {
;     float tmax = fmaxf(s[0][0], s[1][0]);
; #pragma unroll
;     for (int i = 1; i < 16; ++i) tmax = fmaxf(tmax, fmaxf(s[0][i], s[1][i]));
;     tmax = fmaxf(tmax, xor32(tmax)) + cbias;
;     if (!ALLON) tmax = lane_on ? tmax : -1e30f;
;     const float mn = fmaxf(m, tmax);
;     alpha = ex2(m - mn);
;     m = mn;
;     const float mc = (ALLON || lane_on) ? mn - cbias : 1e30f;
; #pragma unroll
;     for (int st = 0; st < 2; ++st)
; #pragma unroll
;       for (int i = 0; i < 16; ++i) { const float pe = ex2(s[st][i] - mc); psum += pe; s[st][i] = pe; }
;   } else {
;     float tmax = -1e30f;
; #pragma unroll
;     for (int st = 0; st < 2; ++st)
; #pragma unroll
;       for (int i = 0; i < 16; ++i) {
;         const int key = kbase + st * 32 + 8 * (i >> 2) + 4 * lh + (i & 3);
;         float v;
;         if (MODE == 1) {
;           const int dist = qp - key;
;           const bool ok = (ALLON || lane_on) && dist >= 0 && dist < win;
;           const int di = dist < 0 ? 0 : (dist > 128 ? 128 : dist);
;           v = ok ? s[st][i] + tab[di] : -1e30f;
;         } else {
;           v = (16 * key + 31 <= qp) ? s[st][i] : -1e30f;
;         }
;         s[st][i] = v;
;         tmax = fmaxf(tmax, v);
;       }
;     tmax = fmaxf(tmax, xor32(tmax));
.LBB0_985:
	s_andn2_saveexec_b64 s[2:3], s[2:3]
	s_cbranch_execz .LBB0_976
	v_mov_b32_e32 v68, v195
	s_nop 0
	v_and_b32_e32 v152, 31, v68
	v_bfe_u32 v153, v68, 5, 1
	v_mul_u32_u24_e32 v68, 0x110, v152
	v_lshlrev_b32_e32 v70, 4, v153
	v_add3_u32 v150, v69, v68, v70
	ds_read_b128 v[68:71], v150
	ds_read_b128 v[156:159], v150 offset:32
	s_waitcnt lgkmcnt(1)
	v_mfma_f32_32x32x16_bf16 v[80:95], v[68:71], v[160:163], 0
	ds_read_b128 v[68:71], v150 offset:8704
	s_waitcnt lgkmcnt(1)
	v_mfma_f32_32x32x16_bf16 v[80:95], v[156:159], v[164:167], v[80:95]
	ds_read_b128 v[156:159], v150 offset:8736
	s_waitcnt lgkmcnt(1)
	v_mfma_f32_32x32x16_bf16 v[64:79], v[68:71], v[160:163], 0
	s_waitcnt lgkmcnt(0)
	v_mfma_f32_32x32x16_bf16 v[64:79], v[156:159], v[164:167], v[64:79]
	ds_read_b128 v[120:123], v150 offset:64
	ds_read_b128 v[156:159], v150 offset:8800
	s_waitcnt lgkmcnt(1)
	v_mfma_f32_32x32x16_bf16 v[80:95], v[120:123], v[168:171], v[80:95]
	ds_read_b128 v[120:123], v150 offset:8768
	s_waitcnt lgkmcnt(0)
	v_mfma_f32_32x32x16_bf16 v[64:79], v[120:123], v[168:171], v[64:79]
	ds_read_b128 v[116:119], v150 offset:96
	v_mov_b32_e32 v120, 0xf149f2ca
	s_waitcnt lgkmcnt(0)
	v_mfma_f32_32x32x16_bf16 v[80:95], v[116:119], v[172:175], v[80:95]
	v_lshlrev_b32_e32 v116, 2, v153
	v_sub_u32_e32 v123, v127, v116
	v_add_u32_e32 v117, 59, v123
	v_mov_b32_e32 v245, 0x1e014
	v_lshl_add_u32 v244, v117, 2, v245
	v_mov_b32_e32 v116, 0xf149f2ca
	v_mfma_f32_32x32x16_bf16 v[64:79], v[156:159], v[172:175], v[64:79]
	ds_read2_b32 v[196:197], v244 offset0:59 offset1:58
	ds_read2_b32 v[198:199], v244 offset0:57 offset1:56
	ds_read2_b32 v[200:201], v244 offset0:51 offset1:50
	ds_read2_b32 v[202:203], v244 offset0:49 offset1:48
	ds_read2_b32 v[204:205], v244 offset0:43 offset1:42
	ds_read2_b32 v[206:207], v244 offset0:41 offset1:40
	ds_read2_b32 v[208:209], v244 offset0:35 offset1:34
	ds_read2_b32 v[210:211], v244 offset0:33 offset1:32
	ds_read2_b32 v[212:213], v244 offset0:27 offset1:26
	ds_read2_b32 v[214:215], v244 offset0:25 offset1:24
	ds_read2_b32 v[216:217], v244 offset0:19 offset1:18
	ds_read2_b32 v[218:219], v244 offset0:17 offset1:16
	ds_read2_b32 v[236:237], v244 offset0:11 offset1:10
	ds_read2_b32 v[238:239], v244 offset0:9 offset1:8
	ds_read2_b32 v[240:241], v244 offset0:3 offset1:2
	s_waitcnt lgkmcnt(14)
	v_add_f32_e32 v120, v80, v196
	v_add_f32_e32 v116, v81, v197
	ds_read2_b32 v[242:243], v244 offset0:1 offset1:0
	s_waitcnt lgkmcnt(14)
	v_add_f32_e32 v119, v82, v198
	v_add_f32_e32 v114, v83, v199
	s_waitcnt lgkmcnt(13)
	v_add_f32_e32 v118, v84, v200
	v_add_f32_e32 v113, v85, v201
	s_waitcnt lgkmcnt(12)
	v_add_f32_e32 v117, v86, v202
	v_add_f32_e32 v112, v87, v203
	s_waitcnt lgkmcnt(11)
	v_add_f32_e32 v115, v88, v204
	v_add_f32_e32 v85, v89, v205
	s_waitcnt lgkmcnt(10)
	v_add_f32_e32 v88, v90, v206
	v_add_f32_e32 v83, v91, v207
	s_waitcnt lgkmcnt(9)
	v_add_f32_e32 v87, v92, v208
	v_add_f32_e32 v81, v93, v209
	s_waitcnt lgkmcnt(8)
	v_add_f32_e32 v86, v94, v210
	v_add_f32_e32 v80, v95, v211
	s_waitcnt lgkmcnt(7)
	v_add_f32_e32 v84, v64, v212
	v_add_f32_e32 v82, v65, v213
	s_waitcnt lgkmcnt(6)
	v_add_f32_e32 v89, v66, v214
	v_add_f32_e32 v65, v67, v215
	s_waitcnt lgkmcnt(5)
	v_add_f32_e32 v67, v68, v216
	v_add_f32_e32 v66, v69, v217
	s_waitcnt lgkmcnt(4)
	v_add_f32_e32 v69, v70, v218
	v_add_f32_e32 v68, v71, v219
	s_waitcnt lgkmcnt(3)
	v_add_f32_e32 v71, v72, v236
	v_add_f32_e32 v70, v73, v237
	s_waitcnt lgkmcnt(2)
	v_add_f32_e32 v73, v74, v238
	v_add_f32_e32 v72, v75, v239
	s_waitcnt lgkmcnt(1)
	v_add_f32_e32 v92, v76, v240
	v_add_f32_e32 v91, v77, v241
	s_waitcnt lgkmcnt(0)
	v_add_f32_e32 v122, v78, v242
	v_add_f32_e32 v121, v79, v243
	v_max3_f32 v64, v120, s93, v116
	v_max3_f32 v64, v64, v119, v114
	v_max3_f32 v64, v64, v118, v113
	v_max3_f32 v64, v64, v117, v112
	v_max3_f32 v64, v64, v115, v85
	v_max3_f32 v64, v64, v88, v83
	v_max3_f32 v64, v64, v87, v81
	v_max3_f32 v64, v64, v86, v80
	v_max3_f32 v64, v64, v84, v82
	v_max3_f32 v64, v64, v89, v65
	v_max3_f32 v64, v64, v67, v66
	v_max3_f32 v64, v64, v69, v68
	v_and_b32_e32 v75, 64, v231
	v_max3_f32 v64, v64, v71, v70
	v_xor_b32_e32 v74, 32, v231
	v_add_u32_e32 v75, 64, v75
	v_max3_f32 v64, v64, v73, v72
	v_cmp_lt_i32_e32 vcc, v74, v75
	v_max3_f32 v64, v64, v92, v91
	v_max3_f32 v64, v64, v122, v121
	v_cndmask_b32_e32 v74, v231, v74, vcc
	v_lshlrev_b32_e32 v74, 2, v74
	ds_bpermute_b32 v74, v74, v64
	s_waitcnt lgkmcnt(0)
	v_max3_f32 v150, v154, v64, v74
	v_sub_f32_e32 v64, v154, v150
	v_exp_f32_e32 v64, v64
	s_nop 0
	v_cmp_neq_f32_e32 vcc, 1.0, v64
	s_cbranch_vccz .LBB0_975
	v_pk_mul_f32 v[62:63], v[62:63], v[64:65] op_sel_hi:[1,0]
	v_pk_mul_f32 v[60:61], v[60:61], v[64:65] op_sel_hi:[1,0]
	v_pk_mul_f32 v[58:59], v[58:59], v[64:65] op_sel_hi:[1,0]
	v_pk_mul_f32 v[56:57], v[56:57], v[64:65] op_sel_hi:[1,0]
	v_pk_mul_f32 v[54:55], v[54:55], v[64:65] op_sel_hi:[1,0]
	v_pk_mul_f32 v[52:53], v[52:53], v[64:65] op_sel_hi:[1,0]
	v_pk_mul_f32 v[50:51], v[50:51], v[64:65] op_sel_hi:[1,0]
	v_pk_mul_f32 v[48:49], v[48:49], v[64:65] op_sel_hi:[1,0]
	v_pk_mul_f32 v[46:47], v[46:47], v[64:65] op_sel_hi:[1,0]
	v_pk_mul_f32 v[44:45], v[44:45], v[64:65] op_sel_hi:[1,0]
	v_pk_mul_f32 v[42:43], v[42:43], v[64:65] op_sel_hi:[1,0]
	v_pk_mul_f32 v[40:41], v[40:41], v[64:65] op_sel_hi:[1,0]
	v_pk_mul_f32 v[38:39], v[38:39], v[64:65] op_sel_hi:[1,0]
	v_pk_mul_f32 v[36:37], v[36:37], v[64:65] op_sel_hi:[1,0]
	v_pk_mul_f32 v[34:35], v[34:35], v[64:65] op_sel_hi:[1,0]
	v_pk_mul_f32 v[32:33], v[32:33], v[64:65] op_sel_hi:[1,0]
	v_pk_mul_f32 v[30:31], v[30:31], v[64:65] op_sel_hi:[1,0]
	v_pk_mul_f32 v[28:29], v[28:29], v[64:65] op_sel_hi:[1,0]
	v_pk_mul_f32 v[26:27], v[26:27], v[64:65] op_sel_hi:[1,0]
	v_pk_mul_f32 v[24:25], v[24:25], v[64:65] op_sel_hi:[1,0]
	v_pk_mul_f32 v[22:23], v[22:23], v[64:65] op_sel_hi:[1,0]
	v_pk_mul_f32 v[20:21], v[20:21], v[64:65] op_sel_hi:[1,0]
	v_pk_mul_f32 v[18:19], v[18:19], v[64:65] op_sel_hi:[1,0]
	v_pk_mul_f32 v[16:17], v[16:17], v[64:65] op_sel_hi:[1,0]
	v_pk_mul_f32 v[14:15], v[14:15], v[64:65] op_sel_hi:[1,0]
	v_pk_mul_f32 v[12:13], v[12:13], v[64:65] op_sel_hi:[1,0]
	v_pk_mul_f32 v[10:11], v[10:11], v[64:65] op_sel_hi:[1,0]
	v_pk_mul_f32 v[8:9], v[8:9], v[64:65] op_sel_hi:[1,0]
	v_pk_mul_f32 v[6:7], v[6:7], v[64:65] op_sel_hi:[1,0]
	v_pk_mul_f32 v[4:5], v[4:5], v[64:65] op_sel_hi:[1,0]
	v_pk_mul_f32 v[2:3], v[2:3], v[64:65] op_sel_hi:[1,0]
	v_pk_mul_f32 v[0:1], v[0:1], v[64:65] op_sel_hi:[1,0]
	s_branch .LBB0_975
